# nt read-once loads plus nt stores for the FFN activation (ACT) and the final output only
# baseline (speedup 1.0000x reference)
; __device__ __forceinline__ float fsilu(float x) { return x * fsigmoid(x); }
; __device__ __forceinline__ u32x4 pack8(f32x4 a, f32x4 b) { u32x4 w; w.x = cvt_pk_bf16(a[0], a[1]); w.y = cvt_pk_bf16(a[2], a[3]); w.z = cvt_pk_bf16(b[0], b[1]); w.w = cvt_pk_bf16(b[2], b[3]); return w; }
;     __device__ __forceinline__ void operator()(AccRef acc, const Unit& u, int wr, int wc, int fr, int fq) const {
;         const int row0 = u.pm * BM + wr * 64 + fr, col0 = u.pn * 128 + wc * 32 + 8 * fq;
; #pragma unroll
;         for (int ai = 0; ai < 2; ++ai)
; #pragma unroll
;             for (int m = 0; m < 4; ++m) {
;                 bf16_t* p = O + (size_t)(row0 + ai * HALF + m * 16) * FF + col0;
;                 f32x4 v0, v1;
; #pragma unroll
;                 for (int j = 0; j < 4; ++j) { v0[j] = fsilu(acc[ai][0][m][0][j]) * acc[ai][1][m][0][j]; v1[j] = fsilu(acc[ai][0][m][1][j]) * acc[ai][1][m][1][j]; }
;                 *(u32x4*)p = pack8(v0, v1);
.LBB0_153:
	s_lshl_b32 s11, s18, 8
	v_mov_b32_e32 v144, v147
	v_mov_b32_e32 v145, v146
	s_add_i32 s11, s11, s40
	s_andn2_b64 vcc, exec, s[0:1]
	v_add_u32_e32 v152, s11, v145
	s_lshl_b32 s11, s49, 7
	s_or_b32 s11, s11, s41
	v_lshl_add_u32 v154, v144, 3, s11
	v_mul_f32_e32 v144, 0xbfb8aa3b, v124
	v_exp_f32_e32 v153, v144
	v_mul_f32_e32 v144, 0xbfb8aa3b, v120
	v_exp_f32_e32 v156, v144
	v_ashrrev_i32_e32 v155, 31, v154
	v_add_f32_e32 v153, 1.0, v153
	v_rcp_f32_e32 v153, v153
	v_add_f32_e32 v156, 1.0, v156
	v_rcp_f32_e32 v158, v156
	v_mov_b64_e32 v[144:145], s[4:5]
	v_mul_f32_e32 v124, v124, v153
	v_mul_f32_e32 v116, v124, v116
	v_mul_f32_e32 v124, 0xbfb8aa3b, v125
	v_exp_f32_e32 v124, v124
	v_mul_f32_e32 v153, 0xbfb8aa3b, v121
	v_exp_f32_e32 v153, v153
	v_mul_f32_e32 v120, v120, v158
	v_mul_f32_e32 v120, v120, v112
	v_add_f32_e32 v112, 1.0, v124
	v_rcp_f32_e32 v112, v112
	v_add_f32_e32 v124, 1.0, v153
	v_mul_f32_e32 v153, 0xbfb8aa3b, v126
	v_rcp_f32_e32 v124, v124
	v_exp_f32_e32 v153, v153
	v_mul_f32_e32 v112, v125, v112
	v_mul_f32_e32 v117, v112, v117
	v_mul_f32_e32 v112, v121, v124
	v_add_f32_e32 v121, 1.0, v153
	v_rcp_f32_e32 v121, v121
	v_mul_f32_e32 v124, 0xbfb8aa3b, v122
	v_exp_f32_e32 v124, v124
	v_mul_f32_e32 v125, v112, v113
	v_mul_f32_e32 v112, v126, v121
	v_mul_f32_e32 v113, 0xbfb8aa3b, v127
	v_mul_f32_e32 v121, v112, v118
	v_exp_f32_e32 v113, v113
	v_mul_f32_e32 v118, 0xbfb8aa3b, v123
	v_exp_f32_e32 v118, v118
	v_add_f32_e32 v112, 1.0, v124
	v_rcp_f32_e32 v112, v112
	v_add_f32_e32 v113, 1.0, v113
	v_rcp_f32_e32 v113, v113
	v_add_f32_e32 v118, 1.0, v118
	v_rcp_f32_e32 v118, v118
	v_mul_f32_e32 v112, v122, v112
	v_mul_f32_e32 v122, v112, v114
	v_mul_f32_e32 v112, v127, v113
	v_mul_f32_e32 v124, v112, v119
	v_mul_f32_e32 v112, v123, v118
	v_mad_i64_i32 v[156:157], s[20:21], v152, s48, v[144:145]
	v_mul_f32_e32 v123, v112, v115
	v_lshlrev_b64 v[112:113], 1, v[154:155]
	v_lshl_add_u64 v[118:119], v[156:157], 0, v[112:113]
	s_nop 1
	v_cvt_pk_bf16_f32 v114, v116, v117
	s_nop 1
	v_cvt_pk_bf16_f32 v115, v121, v124
	s_nop 1
	v_cvt_pk_bf16_f32 v116, v120, v125
	s_nop 1
	v_cvt_pk_bf16_f32 v117, v122, v123
	flat_store_dwordx4 v[118:119], v[114:117] nt
	s_mov_b64 s[0:1], -1
	s_nop 0
	v_mul_f32_e32 v114, 0xbfb8aa3b, v108
	v_exp_f32_e32 v114, v114
	v_mul_f32_e32 v115, 0xbfb8aa3b, v104
	v_exp_f32_e32 v115, v115
	v_add_u32_e32 v116, 16, v152
	v_add_f32_e32 v114, 1.0, v114
	v_rcp_f32_e32 v117, v114
	v_add_f32_e32 v114, 1.0, v115
	v_rcp_f32_e32 v118, v114
	v_mad_i64_i32 v[114:115], s[20:21], v116, s48, v[144:145]
	v_mul_f32_e32 v108, v108, v117
	v_mul_f32_e32 v108, v108, v100
	v_mul_f32_e32 v100, v104, v118
	v_mul_f32_e32 v104, 0xbfb8aa3b, v109
	v_exp_f32_e32 v104, v104
	v_mul_f32_e32 v116, 0xbfb8aa3b, v105
	v_mul_f32_e32 v117, v100, v96
	v_exp_f32_e32 v116, v116
	v_add_f32_e32 v96, 1.0, v104
	v_rcp_f32_e32 v96, v96
	v_mul_f32_e32 v104, 0xbfb8aa3b, v110
	v_exp_f32_e32 v104, v104
	v_add_f32_e32 v100, 1.0, v116
	v_mul_f32_e32 v96, v109, v96
	v_rcp_f32_e32 v100, v100
	v_mul_f32_e32 v96, v96, v101
	v_add_f32_e32 v101, 1.0, v104
	v_rcp_f32_e32 v101, v101
	v_mul_f32_e32 v100, v105, v100
	v_mul_f32_e32 v104, 0xbfb8aa3b, v106
	v_mul_f32_e32 v105, v100, v97
	v_mul_f32_e32 v97, v110, v101
	v_exp_f32_e32 v104, v104
	v_mul_f32_e32 v97, v97, v102
	v_mul_f32_e32 v101, 0xbfb8aa3b, v111
	v_mul_f32_e32 v102, 0xbfb8aa3b, v107
	v_exp_f32_e32 v101, v101
	v_exp_f32_e32 v102, v102
	v_add_f32_e32 v100, 1.0, v104
	v_rcp_f32_e32 v100, v100
	v_add_f32_e32 v101, 1.0, v101
	v_add_f32_e32 v102, 1.0, v102
	v_rcp_f32_e32 v101, v101
	v_rcp_f32_e32 v102, v102
	v_mul_f32_e32 v100, v106, v100
	v_mul_f32_e32 v104, v100, v98
	v_mul_f32_e32 v98, v111, v101
	v_mul_f32_e32 v100, v107, v102
	v_mul_f32_e32 v98, v98, v103
	v_mul_f32_e32 v99, v100, v99
	v_lshl_add_u64 v[100:101], v[114:115], 0, v[112:113]
	s_nop 1
	v_cvt_pk_bf16_f32 v96, v108, v96
	s_nop 1
	v_cvt_pk_bf16_f32 v97, v97, v98
	s_nop 1
	v_cvt_pk_bf16_f32 v98, v117, v105
	s_nop 1
	v_cvt_pk_bf16_f32 v99, v104, v99
	flat_store_dwordx4 v[100:101], v[96:99] nt
	s_nop 1
	v_mul_f32_e32 v96, 0xbfb8aa3b, v92
	v_exp_f32_e32 v96, v96
	v_mul_f32_e32 v97, 0xbfb8aa3b, v88
	v_exp_f32_e32 v97, v97
	v_add_u32_e32 v98, 32, v152
	v_add_f32_e32 v96, 1.0, v96
	v_rcp_f32_e32 v99, v96
	v_add_f32_e32 v96, 1.0, v97
	v_rcp_f32_e32 v100, v96
	v_mad_i64_i32 v[96:97], s[20:21], v98, s48, v[144:145]
	v_mul_f32_e32 v92, v92, v99
	v_mul_f32_e32 v92, v92, v84
	v_mul_f32_e32 v84, v88, v100
	v_mul_f32_e32 v88, 0xbfb8aa3b, v93
	v_exp_f32_e32 v88, v88
	v_mul_f32_e32 v98, 0xbfb8aa3b, v89
	v_mul_f32_e32 v99, v84, v80
	v_exp_f32_e32 v98, v98
	v_add_f32_e32 v80, 1.0, v88
	v_rcp_f32_e32 v80, v80
	v_mul_f32_e32 v88, 0xbfb8aa3b, v94
	v_exp_f32_e32 v88, v88
	v_add_f32_e32 v84, 1.0, v98
	v_mul_f32_e32 v80, v93, v80
	v_rcp_f32_e32 v84, v84
	v_mul_f32_e32 v80, v80, v85
	v_add_f32_e32 v85, 1.0, v88
	v_rcp_f32_e32 v85, v85
	v_mul_f32_e32 v84, v89, v84
	v_mul_f32_e32 v88, 0xbfb8aa3b, v90
	v_mul_f32_e32 v89, v84, v81
	v_mul_f32_e32 v81, v94, v85
	v_exp_f32_e32 v88, v88
	v_mul_f32_e32 v81, v81, v86
	v_mul_f32_e32 v85, 0xbfb8aa3b, v95
	v_mul_f32_e32 v86, 0xbfb8aa3b, v91
	v_exp_f32_e32 v85, v85
	v_exp_f32_e32 v86, v86
	v_add_f32_e32 v84, 1.0, v88
	v_rcp_f32_e32 v84, v84
	v_add_f32_e32 v85, 1.0, v85
	v_add_f32_e32 v86, 1.0, v86
	v_rcp_f32_e32 v85, v85
	v_rcp_f32_e32 v86, v86
	v_mul_f32_e32 v84, v90, v84
	v_mul_f32_e32 v88, v84, v82
	v_mul_f32_e32 v82, v95, v85
	v_mul_f32_e32 v84, v91, v86
	v_mul_f32_e32 v82, v82, v87
	v_mul_f32_e32 v83, v84, v83
	v_lshl_add_u64 v[84:85], v[96:97], 0, v[112:113]
	s_nop 1
	v_cvt_pk_bf16_f32 v80, v92, v80
	s_nop 1
	v_cvt_pk_bf16_f32 v81, v81, v82
	s_nop 1
; __device__ __forceinline__ float fsilu(float x) { return x * fsigmoid(x); }
; __device__ __forceinline__ u32x4 pack8(f32x4 a, f32x4 b) { u32x4 w; w.x = cvt_pk_bf16(a[0], a[1]); w.y = cvt_pk_bf16(a[2], a[3]); w.z = cvt_pk_bf16(b[0], b[1]); w.w = cvt_pk_bf16(b[2], b[3]); return w; }
;     __device__ __forceinline__ void operator()(AccRef acc, const Unit& u, int wr, int wc, int fr, int fq) const {
;         const int row0 = u.pm * BM + wr * 64 + fr, col0 = u.pn * 128 + wc * 32 + 8 * fq;
; #pragma unroll
;         for (int ai = 0; ai < 2; ++ai)
; #pragma unroll
;             for (int m = 0; m < 4; ++m) {
;                 bf16_t* p = O + (size_t)(row0 + ai * HALF + m * 16) * FF + col0;
;                 f32x4 v0, v1;
; #pragma unroll
;                 for (int j = 0; j < 4; ++j) { v0[j] = fsilu(acc[ai][0][m][0][j]) * acc[ai][1][m][0][j]; v1[j] = fsilu(acc[ai][0][m][1][j]) * acc[ai][1][m][1][j]; }
;                 *(u32x4*)p = pack8(v0, v1);
	v_cvt_pk_bf16_f32 v82, v99, v89
	s_nop 1
	v_cvt_pk_bf16_f32 v83, v88, v83
	flat_store_dwordx4 v[84:85], v[80:83] nt
	s_nop 1
	v_mul_f32_e32 v80, 0xbfb8aa3b, v76
	v_exp_f32_e32 v80, v80
	v_mul_f32_e32 v81, 0xbfb8aa3b, v72
	v_exp_f32_e32 v81, v81
	v_add_u32_e32 v82, 48, v152
	v_add_f32_e32 v80, 1.0, v80
	v_rcp_f32_e32 v83, v80
	v_add_f32_e32 v80, 1.0, v81
	v_rcp_f32_e32 v84, v80
	v_mad_i64_i32 v[80:81], s[20:21], v82, s48, v[144:145]
	v_mul_f32_e32 v76, v76, v83
	v_mul_f32_e32 v76, v76, v68
	v_mul_f32_e32 v68, v72, v84
	v_mul_f32_e32 v72, 0xbfb8aa3b, v77
	v_exp_f32_e32 v72, v72
	v_mul_f32_e32 v82, 0xbfb8aa3b, v73
	v_mul_f32_e32 v83, v68, v64
	v_exp_f32_e32 v82, v82
	v_add_f32_e32 v64, 1.0, v72
	v_rcp_f32_e32 v64, v64
	v_mul_f32_e32 v72, 0xbfb8aa3b, v78
	v_exp_f32_e32 v72, v72
	v_add_f32_e32 v68, 1.0, v82
	v_mul_f32_e32 v64, v77, v64
	v_rcp_f32_e32 v68, v68
	v_mul_f32_e32 v64, v64, v69
	v_add_f32_e32 v69, 1.0, v72
	v_rcp_f32_e32 v69, v69
	v_mul_f32_e32 v68, v73, v68
	v_mul_f32_e32 v72, 0xbfb8aa3b, v74
	v_mul_f32_e32 v73, v68, v65
	v_mul_f32_e32 v65, v78, v69
	v_exp_f32_e32 v72, v72
	v_mul_f32_e32 v65, v65, v70
	v_mul_f32_e32 v69, 0xbfb8aa3b, v79
	v_mul_f32_e32 v70, 0xbfb8aa3b, v75
	v_exp_f32_e32 v69, v69
	v_exp_f32_e32 v70, v70
	v_add_f32_e32 v68, 1.0, v72
	v_rcp_f32_e32 v68, v68
	v_add_f32_e32 v69, 1.0, v69
	v_add_f32_e32 v70, 1.0, v70
	v_rcp_f32_e32 v69, v69
	v_rcp_f32_e32 v70, v70
	v_mul_f32_e32 v68, v74, v68
	v_mul_f32_e32 v72, v68, v66
	v_mul_f32_e32 v66, v79, v69
	v_mul_f32_e32 v68, v75, v70
	v_mul_f32_e32 v66, v66, v71
	v_mul_f32_e32 v67, v68, v67
	v_lshl_add_u64 v[68:69], v[80:81], 0, v[112:113]
	s_nop 1
	v_cvt_pk_bf16_f32 v64, v76, v64
	s_nop 1
	v_cvt_pk_bf16_f32 v65, v65, v66
	s_nop 1
	v_cvt_pk_bf16_f32 v66, v83, v73
	s_nop 1
	v_cvt_pk_bf16_f32 v67, v72, v67
	flat_store_dwordx4 v[68:69], v[64:67] nt
	s_nop 1
	v_mul_f32_e32 v64, 0xbfb8aa3b, v60
	v_exp_f32_e32 v64, v64
	v_mul_f32_e32 v65, 0xbfb8aa3b, v56
	v_exp_f32_e32 v65, v65
	v_add_u32_e32 v66, 0x80, v152
	v_add_f32_e32 v64, 1.0, v64
	v_rcp_f32_e32 v67, v64
	v_add_f32_e32 v64, 1.0, v65
	v_rcp_f32_e32 v68, v64
	v_mad_i64_i32 v[64:65], s[20:21], v66, s48, v[144:145]
	v_mul_f32_e32 v60, v60, v67
	v_mul_f32_e32 v60, v60, v52
	v_mul_f32_e32 v52, v56, v68
	v_mul_f32_e32 v56, 0xbfb8aa3b, v61
	v_exp_f32_e32 v56, v56
	v_mul_f32_e32 v66, 0xbfb8aa3b, v57
	v_mul_f32_e32 v67, v52, v48
	v_exp_f32_e32 v66, v66
	v_add_f32_e32 v48, 1.0, v56
	v_rcp_f32_e32 v48, v48
	v_mul_f32_e32 v56, 0xbfb8aa3b, v62
	v_exp_f32_e32 v56, v56
	v_add_f32_e32 v52, 1.0, v66
	v_mul_f32_e32 v48, v61, v48
	v_rcp_f32_e32 v52, v52
	v_mul_f32_e32 v48, v48, v53
	v_add_f32_e32 v53, 1.0, v56
	v_rcp_f32_e32 v53, v53
	v_mul_f32_e32 v52, v57, v52
	v_mul_f32_e32 v56, 0xbfb8aa3b, v58
	v_mul_f32_e32 v57, v52, v49
	v_mul_f32_e32 v49, v62, v53
	v_exp_f32_e32 v56, v56
	v_mul_f32_e32 v49, v49, v54
	v_mul_f32_e32 v53, 0xbfb8aa3b, v63
	v_mul_f32_e32 v54, 0xbfb8aa3b, v59
	v_exp_f32_e32 v53, v53
	v_exp_f32_e32 v54, v54
	v_add_f32_e32 v52, 1.0, v56
	v_rcp_f32_e32 v52, v52
	v_add_f32_e32 v53, 1.0, v53
	v_add_f32_e32 v54, 1.0, v54
	v_rcp_f32_e32 v53, v53
	v_rcp_f32_e32 v54, v54
	v_mul_f32_e32 v52, v58, v52
	v_mul_f32_e32 v56, v52, v50
	v_mul_f32_e32 v50, v63, v53
	v_mul_f32_e32 v52, v59, v54
	v_mul_f32_e32 v50, v50, v55
	v_mul_f32_e32 v51, v52, v51
	v_lshl_add_u64 v[52:53], v[64:65], 0, v[112:113]
	s_nop 1
	v_cvt_pk_bf16_f32 v48, v60, v48
	s_nop 1
	v_cvt_pk_bf16_f32 v49, v49, v50
	s_nop 1
	v_cvt_pk_bf16_f32 v50, v67, v57
	s_nop 1
	v_cvt_pk_bf16_f32 v51, v56, v51
	flat_store_dwordx4 v[52:53], v[48:51] nt
	s_nop 1
	v_mul_f32_e32 v48, 0xbfb8aa3b, v44
	v_exp_f32_e32 v48, v48
	v_mul_f32_e32 v49, 0xbfb8aa3b, v40
	v_exp_f32_e32 v49, v49
	v_add_u32_e32 v50, 0x90, v152
	v_add_f32_e32 v48, 1.0, v48
	v_rcp_f32_e32 v51, v48
	v_add_f32_e32 v48, 1.0, v49
	v_rcp_f32_e32 v52, v48
	v_mad_i64_i32 v[48:49], s[20:21], v50, s48, v[144:145]
	v_mul_f32_e32 v44, v44, v51
	v_mul_f32_e32 v44, v44, v36
	v_mul_f32_e32 v36, v40, v52
	v_mul_f32_e32 v40, 0xbfb8aa3b, v45
	v_exp_f32_e32 v40, v40
	v_mul_f32_e32 v50, 0xbfb8aa3b, v41
	v_mul_f32_e32 v51, v36, v32
	v_exp_f32_e32 v50, v50
	v_add_f32_e32 v32, 1.0, v40
	v_rcp_f32_e32 v32, v32
	v_mul_f32_e32 v40, 0xbfb8aa3b, v46
	v_exp_f32_e32 v40, v40
	v_add_f32_e32 v36, 1.0, v50
	v_mul_f32_e32 v32, v45, v32
	v_rcp_f32_e32 v36, v36
	v_mul_f32_e32 v32, v32, v37
	v_add_f32_e32 v37, 1.0, v40
; __device__ __forceinline__ float fsilu(float x) { return x * fsigmoid(x); }
; __device__ __forceinline__ u32x4 pack8(f32x4 a, f32x4 b) { u32x4 w; w.x = cvt_pk_bf16(a[0], a[1]); w.y = cvt_pk_bf16(a[2], a[3]); w.z = cvt_pk_bf16(b[0], b[1]); w.w = cvt_pk_bf16(b[2], b[3]); return w; }
; #define PG8_BAR __builtin_amdgcn_s_barrier()
; template <class Epi>
; __device__ __forceinline__ void gemm_phase(ldsp lds, const Gemm g, const StaticOrder& S, const Epi& E, int wave0) {
;     ...
;         if (!has_next) break;
; #pragma unroll
;         for (int a = 0; a < 2; ++a)
; #pragma unroll
;             for (int b = 0; b < 2; ++b)
; #pragma unroll
;                 for (int m = 0; m < 4; ++m)
; #pragma unroll
;                     for (int n = 0; n < 2; ++n) acc[a][b][m][n] = (f32x4){0.f, 0.f, 0.f, 0.f};
;         cur = nxt; cA = nA; cB = nB; ++ui;
;         if (wr == 1) PG8_BAR;
;     __device__ __forceinline__ void operator()(AccRef acc, const Unit& u, int wr, int wc, int fr, int fq) const {
;     ...
;         for (int ai = 0; ai < 2; ++ai)
; #pragma unroll
;             for (int m = 0; m < 4; ++m) {
;                 bf16_t* p = O + (size_t)(row0 + ai * HALF + m * 16) * FF + col0;
;                 f32x4 v0, v1;
; #pragma unroll
;                 for (int j = 0; j < 4; ++j) { v0[j] = fsilu(acc[ai][0][m][0][j]) * acc[ai][1][m][0][j]; v1[j] = fsilu(acc[ai][0][m][1][j]) * acc[ai][1][m][1][j]; }
;                 *(u32x4*)p = pack8(v0, v1);
	v_rcp_f32_e32 v37, v37
	v_mul_f32_e32 v36, v41, v36
	v_mul_f32_e32 v40, 0xbfb8aa3b, v42
	v_mul_f32_e32 v41, v36, v33
	v_mul_f32_e32 v33, v46, v37
	v_exp_f32_e32 v40, v40
	v_mul_f32_e32 v33, v33, v38
	v_mul_f32_e32 v37, 0xbfb8aa3b, v47
	v_mul_f32_e32 v38, 0xbfb8aa3b, v43
	v_exp_f32_e32 v37, v37
	v_exp_f32_e32 v38, v38
	v_add_f32_e32 v36, 1.0, v40
	v_rcp_f32_e32 v36, v36
	v_add_f32_e32 v37, 1.0, v37
	v_add_f32_e32 v38, 1.0, v38
	v_rcp_f32_e32 v37, v37
	v_rcp_f32_e32 v38, v38
	v_mul_f32_e32 v36, v42, v36
	v_mul_f32_e32 v40, v36, v34
	v_mul_f32_e32 v34, v47, v37
	v_mul_f32_e32 v36, v43, v38
	v_mul_f32_e32 v34, v34, v39
	v_mul_f32_e32 v35, v36, v35
	v_lshl_add_u64 v[36:37], v[48:49], 0, v[112:113]
	s_nop 1
	v_cvt_pk_bf16_f32 v32, v44, v32
	s_nop 1
	v_cvt_pk_bf16_f32 v33, v33, v34
	s_nop 1
	v_cvt_pk_bf16_f32 v34, v51, v41
	s_nop 1
	v_cvt_pk_bf16_f32 v35, v40, v35
	flat_store_dwordx4 v[36:37], v[32:35] nt
	s_nop 1
	v_mul_f32_e32 v32, 0xbfb8aa3b, v28
	v_exp_f32_e32 v32, v32
	v_mul_f32_e32 v33, 0xbfb8aa3b, v24
	v_exp_f32_e32 v33, v33
	v_add_u32_e32 v34, 0xa0, v152
	v_add_f32_e32 v32, 1.0, v32
	v_rcp_f32_e32 v35, v32
	v_add_f32_e32 v32, 1.0, v33
	v_rcp_f32_e32 v36, v32
	v_mad_i64_i32 v[32:33], s[20:21], v34, s48, v[144:145]
	v_mul_f32_e32 v28, v28, v35
	v_mul_f32_e32 v28, v28, v20
	v_mul_f32_e32 v20, v24, v36
	v_mul_f32_e32 v24, 0xbfb8aa3b, v29
	v_exp_f32_e32 v24, v24
	v_mul_f32_e32 v34, 0xbfb8aa3b, v25
	v_mul_f32_e32 v35, v20, v16
	v_exp_f32_e32 v34, v34
	v_add_f32_e32 v16, 1.0, v24
	v_rcp_f32_e32 v16, v16
	v_mul_f32_e32 v24, 0xbfb8aa3b, v30
	v_exp_f32_e32 v24, v24
	v_add_f32_e32 v20, 1.0, v34
	v_mul_f32_e32 v16, v29, v16
	v_rcp_f32_e32 v20, v20
	v_mul_f32_e32 v16, v16, v21
	v_add_f32_e32 v21, 1.0, v24
	v_rcp_f32_e32 v21, v21
	v_mul_f32_e32 v20, v25, v20
	v_mul_f32_e32 v24, 0xbfb8aa3b, v26
	v_mul_f32_e32 v25, v20, v17
	v_mul_f32_e32 v17, v30, v21
	v_exp_f32_e32 v24, v24
	v_mul_f32_e32 v17, v17, v22
	v_mul_f32_e32 v21, 0xbfb8aa3b, v31
	v_mul_f32_e32 v22, 0xbfb8aa3b, v27
	v_exp_f32_e32 v21, v21
	v_exp_f32_e32 v22, v22
	v_add_f32_e32 v20, 1.0, v24
	v_rcp_f32_e32 v20, v20
	v_add_f32_e32 v21, 1.0, v21
	v_add_f32_e32 v22, 1.0, v22
	v_rcp_f32_e32 v21, v21
	v_rcp_f32_e32 v22, v22
	v_mul_f32_e32 v20, v26, v20
	v_mul_f32_e32 v24, v20, v18
	v_mul_f32_e32 v18, v31, v21
	v_mul_f32_e32 v20, v27, v22
	v_mul_f32_e32 v18, v18, v23
	v_mul_f32_e32 v19, v20, v19
	v_lshl_add_u64 v[20:21], v[32:33], 0, v[112:113]
	s_nop 1
	v_cvt_pk_bf16_f32 v16, v28, v16
	s_nop 1
	v_cvt_pk_bf16_f32 v17, v17, v18
	s_nop 1
	v_cvt_pk_bf16_f32 v18, v35, v25
	s_nop 1
	v_cvt_pk_bf16_f32 v19, v24, v19
	flat_store_dwordx4 v[20:21], v[16:19] nt
	s_nop 1
	v_mul_f32_e32 v16, 0xbfb8aa3b, v12
	v_exp_f32_e32 v16, v16
	v_mul_f32_e32 v17, 0xbfb8aa3b, v8
	v_exp_f32_e32 v17, v17
	v_add_u32_e32 v18, 0xb0, v152
	v_add_f32_e32 v16, 1.0, v16
	v_rcp_f32_e32 v19, v16
	v_add_f32_e32 v16, 1.0, v17
	v_rcp_f32_e32 v20, v16
	v_mad_i64_i32 v[16:17], s[20:21], v18, s48, v[144:145]
	v_mul_f32_e32 v12, v12, v19
	v_mul_f32_e32 v12, v12, v4
	v_mul_f32_e32 v4, v8, v20
	v_mul_f32_e32 v8, 0xbfb8aa3b, v13
	v_exp_f32_e32 v8, v8
	v_mul_f32_e32 v18, 0xbfb8aa3b, v9
	v_mul_f32_e32 v19, v4, v0
	v_exp_f32_e32 v18, v18
	v_add_f32_e32 v0, 1.0, v8
	v_rcp_f32_e32 v0, v0
	v_mul_f32_e32 v8, 0xbfb8aa3b, v14
	v_exp_f32_e32 v8, v8
	v_add_f32_e32 v4, 1.0, v18
	v_mul_f32_e32 v0, v13, v0
	v_rcp_f32_e32 v4, v4
	v_mul_f32_e32 v0, v0, v5
	v_add_f32_e32 v5, 1.0, v8
	v_rcp_f32_e32 v5, v5
	v_mul_f32_e32 v4, v9, v4
	v_mul_f32_e32 v8, 0xbfb8aa3b, v10
	v_mul_f32_e32 v9, v4, v1
	v_mul_f32_e32 v1, v14, v5
	v_exp_f32_e32 v8, v8
	v_mul_f32_e32 v1, v1, v6
	v_mul_f32_e32 v5, 0xbfb8aa3b, v15
	v_mul_f32_e32 v6, 0xbfb8aa3b, v11
	v_exp_f32_e32 v5, v5
	v_exp_f32_e32 v6, v6
	v_add_f32_e32 v4, 1.0, v8
	v_rcp_f32_e32 v4, v4
	v_add_f32_e32 v5, 1.0, v5
	v_add_f32_e32 v6, 1.0, v6
	v_rcp_f32_e32 v5, v5
	v_rcp_f32_e32 v6, v6
	v_mul_f32_e32 v4, v10, v4
	v_mul_f32_e32 v8, v4, v2
	v_mul_f32_e32 v2, v15, v5
	v_mul_f32_e32 v4, v11, v6
	v_mul_f32_e32 v2, v2, v7
	v_mul_f32_e32 v3, v4, v3
	v_lshl_add_u64 v[4:5], v[16:17], 0, v[112:113]
	s_nop 1
	v_cvt_pk_bf16_f32 v0, v12, v0
	s_nop 1
	v_cvt_pk_bf16_f32 v1, v1, v2
	s_nop 1
	v_cvt_pk_bf16_f32 v2, v19, v9
	s_nop 1
	v_cvt_pk_bf16_f32 v3, v8, v3
	flat_store_dwordx4 v[4:5], v[0:3] nt
	s_cbranch_vccnz .LBB0_146
	s_andn2_b64 vcc, exec, s[2:3]
	s_cbranch_vccnz .LBB0_145
	s_barrier
	s_branch .LBB0_145

; __device__ __forceinline__ float fsilu(float x) { return x * fsigmoid(x); }
; __device__ __forceinline__ u32x4 pack8(f32x4 a, f32x4 b) { u32x4 w; w.x = cvt_pk_bf16(a[0], a[1]); w.y = cvt_pk_bf16(a[2], a[3]); w.z = cvt_pk_bf16(b[0], b[1]); w.w = cvt_pk_bf16(b[2], b[3]); return w; }
;     __device__ __forceinline__ void operator()(AccRef acc, const Unit& u, int wr, int wc, int fr, int fq) const {
;         const int row0 = u.pm * BM + wr * 64 + fr, col0 = u.pn * 128 + wc * 32 + 8 * fq;
; #pragma unroll
;         for (int ai = 0; ai < 2; ++ai)
; #pragma unroll
;             for (int m = 0; m < 4; ++m) {
;                 bf16_t* p = O + (size_t)(row0 + ai * HALF + m * 16) * FF + col0;
;                 f32x4 v0, v1;
; #pragma unroll
;                 for (int j = 0; j < 4; ++j) { v0[j] = fsilu(acc[ai][0][m][0][j]) * acc[ai][1][m][0][j]; v1[j] = fsilu(acc[ai][0][m][1][j]) * acc[ai][1][m][1][j]; }
;                 *(u32x4*)p = pack8(v0, v1);
.LBB0_892:
	v_mov_b32_e32 v144, v146
	v_mov_b32_e32 v145, v147
	s_lshl_b32 s11, s18, 8
	s_add_i32 s11, s11, s40
	v_add_u32_e32 v152, s11, v144
	v_mul_f32_e32 v144, 0xbfb8aa3b, v124
	v_exp_f32_e32 v153, v144
	v_mul_f32_e32 v144, 0xbfb8aa3b, v120
	v_exp_f32_e32 v156, v144
	s_lshl_b32 s11, s49, 7
	v_add_f32_e32 v153, 1.0, v153
	v_rcp_f32_e32 v153, v153
	v_add_f32_e32 v156, 1.0, v156
	v_rcp_f32_e32 v158, v156
	s_or_b32 s11, s11, s41
	v_mul_f32_e32 v124, v124, v153
	v_mul_f32_e32 v116, v124, v116
	v_mul_f32_e32 v124, 0xbfb8aa3b, v125
	v_exp_f32_e32 v124, v124
	v_mul_f32_e32 v153, 0xbfb8aa3b, v121
	v_exp_f32_e32 v153, v153
	v_mul_f32_e32 v120, v120, v158
	v_mul_f32_e32 v120, v120, v112
	v_add_f32_e32 v112, 1.0, v124
	v_rcp_f32_e32 v112, v112
	v_add_f32_e32 v124, 1.0, v153
	v_mul_f32_e32 v153, 0xbfb8aa3b, v126
	v_rcp_f32_e32 v124, v124
	v_exp_f32_e32 v153, v153
	v_mul_f32_e32 v112, v125, v112
	v_mul_f32_e32 v117, v112, v117
	v_mul_f32_e32 v112, v121, v124
	v_add_f32_e32 v121, 1.0, v153
	v_rcp_f32_e32 v121, v121
	v_mul_f32_e32 v124, 0xbfb8aa3b, v122
	v_exp_f32_e32 v124, v124
	v_mul_f32_e32 v125, v112, v113
	v_mul_f32_e32 v112, v126, v121
	v_mul_f32_e32 v113, 0xbfb8aa3b, v127
	v_mul_f32_e32 v121, v112, v118
	v_exp_f32_e32 v113, v113
	v_mul_f32_e32 v118, 0xbfb8aa3b, v123
	v_exp_f32_e32 v118, v118
	v_add_f32_e32 v112, 1.0, v124
	v_rcp_f32_e32 v112, v112
	v_add_f32_e32 v113, 1.0, v113
	v_rcp_f32_e32 v113, v113
	v_add_f32_e32 v118, 1.0, v118
	v_rcp_f32_e32 v118, v118
	v_mul_f32_e32 v112, v122, v112
	v_lshl_add_u32 v154, v145, 3, s11
	v_mul_f32_e32 v122, v112, v114
	v_mul_f32_e32 v112, v127, v113
	v_ashrrev_i32_e32 v155, 31, v154
	v_mov_b64_e32 v[144:145], s[4:5]
	v_mul_f32_e32 v124, v112, v119
	v_mul_f32_e32 v112, v123, v118
	v_mad_i64_i32 v[156:157], s[20:21], v152, s48, v[144:145]
	v_mul_f32_e32 v123, v112, v115
	v_lshlrev_b64 v[112:113], 1, v[154:155]
	v_lshl_add_u64 v[118:119], v[156:157], 0, v[112:113]
	s_nop 1
	v_cvt_pk_bf16_f32 v114, v116, v117
	s_nop 1
	v_cvt_pk_bf16_f32 v115, v121, v124
	s_nop 1
	v_cvt_pk_bf16_f32 v116, v120, v125
	s_nop 1
	v_cvt_pk_bf16_f32 v117, v122, v123
	flat_store_dwordx4 v[118:119], v[114:117] nt
	s_andn2_b64 vcc, exec, s[0:1]
	s_mov_b64 s[0:1], -1
	v_mul_f32_e32 v114, 0xbfb8aa3b, v108
	v_exp_f32_e32 v114, v114
	v_mul_f32_e32 v115, 0xbfb8aa3b, v104
	v_exp_f32_e32 v115, v115
	v_add_u32_e32 v116, 16, v152
	v_add_f32_e32 v114, 1.0, v114
	v_rcp_f32_e32 v117, v114
	v_add_f32_e32 v114, 1.0, v115
	v_rcp_f32_e32 v118, v114
	v_mad_i64_i32 v[114:115], s[20:21], v116, s48, v[144:145]
	v_mul_f32_e32 v108, v108, v117
	v_mul_f32_e32 v108, v108, v100
	v_mul_f32_e32 v100, v104, v118
	v_mul_f32_e32 v104, 0xbfb8aa3b, v109
	v_exp_f32_e32 v104, v104
	v_mul_f32_e32 v116, 0xbfb8aa3b, v105
	v_mul_f32_e32 v117, v100, v96
	v_exp_f32_e32 v116, v116
	v_add_f32_e32 v96, 1.0, v104
	v_rcp_f32_e32 v96, v96
	v_mul_f32_e32 v104, 0xbfb8aa3b, v110
	v_exp_f32_e32 v104, v104
	v_add_f32_e32 v100, 1.0, v116
	v_mul_f32_e32 v96, v109, v96
	v_rcp_f32_e32 v100, v100
	v_mul_f32_e32 v96, v96, v101
	v_add_f32_e32 v101, 1.0, v104
	v_rcp_f32_e32 v101, v101
	v_mul_f32_e32 v100, v105, v100
	v_mul_f32_e32 v104, 0xbfb8aa3b, v106
	v_mul_f32_e32 v105, v100, v97
	v_mul_f32_e32 v97, v110, v101
	v_exp_f32_e32 v104, v104
	v_mul_f32_e32 v97, v97, v102
	v_mul_f32_e32 v101, 0xbfb8aa3b, v111
	v_mul_f32_e32 v102, 0xbfb8aa3b, v107
	v_exp_f32_e32 v101, v101
	v_exp_f32_e32 v102, v102
	v_add_f32_e32 v100, 1.0, v104
	v_rcp_f32_e32 v100, v100
	v_add_f32_e32 v101, 1.0, v101
	v_add_f32_e32 v102, 1.0, v102
	v_rcp_f32_e32 v101, v101
	v_rcp_f32_e32 v102, v102
	v_mul_f32_e32 v100, v106, v100
	v_mul_f32_e32 v104, v100, v98
	v_mul_f32_e32 v98, v111, v101
	v_mul_f32_e32 v100, v107, v102
	v_mul_f32_e32 v98, v98, v103
	v_mul_f32_e32 v99, v100, v99
	v_lshl_add_u64 v[100:101], v[114:115], 0, v[112:113]
	s_nop 1
	v_cvt_pk_bf16_f32 v96, v108, v96
	s_nop 1
	v_cvt_pk_bf16_f32 v97, v97, v98
	s_nop 1
	v_cvt_pk_bf16_f32 v98, v117, v105
	s_nop 1
	v_cvt_pk_bf16_f32 v99, v104, v99
	flat_store_dwordx4 v[100:101], v[96:99] nt
	s_nop 1
	v_mul_f32_e32 v96, 0xbfb8aa3b, v92
	v_exp_f32_e32 v96, v96
	v_mul_f32_e32 v97, 0xbfb8aa3b, v88
	v_exp_f32_e32 v97, v97
	v_add_u32_e32 v98, 32, v152
	v_add_f32_e32 v96, 1.0, v96
	v_rcp_f32_e32 v99, v96
	v_add_f32_e32 v96, 1.0, v97
	v_rcp_f32_e32 v100, v96
	v_mad_i64_i32 v[96:97], s[20:21], v98, s48, v[144:145]
	v_mul_f32_e32 v92, v92, v99
	v_mul_f32_e32 v92, v92, v84
	v_mul_f32_e32 v84, v88, v100
	v_mul_f32_e32 v88, 0xbfb8aa3b, v93
	v_exp_f32_e32 v88, v88
	v_mul_f32_e32 v98, 0xbfb8aa3b, v89
	v_mul_f32_e32 v99, v84, v80
	v_exp_f32_e32 v98, v98
	v_add_f32_e32 v80, 1.0, v88
	v_rcp_f32_e32 v80, v80
	v_mul_f32_e32 v88, 0xbfb8aa3b, v94
	v_exp_f32_e32 v88, v88
	v_add_f32_e32 v84, 1.0, v98
	v_mul_f32_e32 v80, v93, v80
	v_rcp_f32_e32 v84, v84
	v_mul_f32_e32 v80, v80, v85
	v_add_f32_e32 v85, 1.0, v88
	v_rcp_f32_e32 v85, v85
	v_mul_f32_e32 v84, v89, v84
	v_mul_f32_e32 v88, 0xbfb8aa3b, v90
	v_mul_f32_e32 v89, v84, v81
	v_mul_f32_e32 v81, v94, v85
	v_exp_f32_e32 v88, v88
	v_mul_f32_e32 v81, v81, v86
	v_mul_f32_e32 v85, 0xbfb8aa3b, v95
	v_mul_f32_e32 v86, 0xbfb8aa3b, v91
	v_exp_f32_e32 v85, v85
	v_exp_f32_e32 v86, v86
	v_add_f32_e32 v84, 1.0, v88
	v_rcp_f32_e32 v84, v84
	v_add_f32_e32 v85, 1.0, v85
	v_add_f32_e32 v86, 1.0, v86
	v_rcp_f32_e32 v85, v85
	v_rcp_f32_e32 v86, v86
	v_mul_f32_e32 v84, v90, v84
	v_mul_f32_e32 v88, v84, v82
	v_mul_f32_e32 v82, v95, v85
	v_mul_f32_e32 v84, v91, v86
	v_mul_f32_e32 v82, v82, v87
	v_mul_f32_e32 v83, v84, v83
	v_lshl_add_u64 v[84:85], v[96:97], 0, v[112:113]
	s_nop 1
	v_cvt_pk_bf16_f32 v80, v92, v80
	s_nop 1
	v_cvt_pk_bf16_f32 v81, v81, v82
	s_nop 1
; __device__ __forceinline__ float fsilu(float x) { return x * fsigmoid(x); }
; __device__ __forceinline__ u32x4 pack8(f32x4 a, f32x4 b) { u32x4 w; w.x = cvt_pk_bf16(a[0], a[1]); w.y = cvt_pk_bf16(a[2], a[3]); w.z = cvt_pk_bf16(b[0], b[1]); w.w = cvt_pk_bf16(b[2], b[3]); return w; }
;     __device__ __forceinline__ void operator()(AccRef acc, const Unit& u, int wr, int wc, int fr, int fq) const {
;         const int row0 = u.pm * BM + wr * 64 + fr, col0 = u.pn * 128 + wc * 32 + 8 * fq;
; #pragma unroll
;         for (int ai = 0; ai < 2; ++ai)
; #pragma unroll
;             for (int m = 0; m < 4; ++m) {
;                 bf16_t* p = O + (size_t)(row0 + ai * HALF + m * 16) * FF + col0;
;                 f32x4 v0, v1;
; #pragma unroll
;                 for (int j = 0; j < 4; ++j) { v0[j] = fsilu(acc[ai][0][m][0][j]) * acc[ai][1][m][0][j]; v1[j] = fsilu(acc[ai][0][m][1][j]) * acc[ai][1][m][1][j]; }
;                 *(u32x4*)p = pack8(v0, v1);
	v_cvt_pk_bf16_f32 v82, v99, v89
	s_nop 1
	v_cvt_pk_bf16_f32 v83, v88, v83
	flat_store_dwordx4 v[84:85], v[80:83] nt
	s_nop 1
	v_mul_f32_e32 v80, 0xbfb8aa3b, v76
	v_exp_f32_e32 v80, v80
	v_mul_f32_e32 v81, 0xbfb8aa3b, v72
	v_exp_f32_e32 v81, v81
	v_add_u32_e32 v82, 48, v152
	v_add_f32_e32 v80, 1.0, v80
	v_rcp_f32_e32 v83, v80
	v_add_f32_e32 v80, 1.0, v81
	v_rcp_f32_e32 v84, v80
	v_mad_i64_i32 v[80:81], s[20:21], v82, s48, v[144:145]
	v_mul_f32_e32 v76, v76, v83
	v_mul_f32_e32 v76, v76, v68
	v_mul_f32_e32 v68, v72, v84
	v_mul_f32_e32 v72, 0xbfb8aa3b, v77
	v_exp_f32_e32 v72, v72
	v_mul_f32_e32 v82, 0xbfb8aa3b, v73
	v_mul_f32_e32 v83, v68, v64
	v_exp_f32_e32 v82, v82
	v_add_f32_e32 v64, 1.0, v72
	v_rcp_f32_e32 v64, v64
	v_mul_f32_e32 v72, 0xbfb8aa3b, v78
	v_exp_f32_e32 v72, v72
	v_add_f32_e32 v68, 1.0, v82
	v_mul_f32_e32 v64, v77, v64
	v_rcp_f32_e32 v68, v68
	v_mul_f32_e32 v64, v64, v69
	v_add_f32_e32 v69, 1.0, v72
	v_rcp_f32_e32 v69, v69
	v_mul_f32_e32 v68, v73, v68
	v_mul_f32_e32 v72, 0xbfb8aa3b, v74
	v_mul_f32_e32 v73, v68, v65
	v_mul_f32_e32 v65, v78, v69
	v_exp_f32_e32 v72, v72
	v_mul_f32_e32 v65, v65, v70
	v_mul_f32_e32 v69, 0xbfb8aa3b, v79
	v_mul_f32_e32 v70, 0xbfb8aa3b, v75
	v_exp_f32_e32 v69, v69
	v_exp_f32_e32 v70, v70
	v_add_f32_e32 v68, 1.0, v72
	v_rcp_f32_e32 v68, v68
	v_add_f32_e32 v69, 1.0, v69
	v_add_f32_e32 v70, 1.0, v70
	v_rcp_f32_e32 v69, v69
	v_rcp_f32_e32 v70, v70
	v_mul_f32_e32 v68, v74, v68
	v_mul_f32_e32 v72, v68, v66
	v_mul_f32_e32 v66, v79, v69
	v_mul_f32_e32 v68, v75, v70
	v_mul_f32_e32 v66, v66, v71
	v_mul_f32_e32 v67, v68, v67
	v_lshl_add_u64 v[68:69], v[80:81], 0, v[112:113]
	s_nop 1
	v_cvt_pk_bf16_f32 v64, v76, v64
	s_nop 1
	v_cvt_pk_bf16_f32 v65, v65, v66
	s_nop 1
	v_cvt_pk_bf16_f32 v66, v83, v73
	s_nop 1
	v_cvt_pk_bf16_f32 v67, v72, v67
	flat_store_dwordx4 v[68:69], v[64:67] nt
	s_nop 1
	v_mul_f32_e32 v64, 0xbfb8aa3b, v60
	v_exp_f32_e32 v64, v64
	v_mul_f32_e32 v65, 0xbfb8aa3b, v56
	v_exp_f32_e32 v65, v65
	v_add_u32_e32 v66, 0x80, v152
	v_add_f32_e32 v64, 1.0, v64
	v_rcp_f32_e32 v67, v64
	v_add_f32_e32 v64, 1.0, v65
	v_rcp_f32_e32 v68, v64
	v_mad_i64_i32 v[64:65], s[20:21], v66, s48, v[144:145]
	v_mul_f32_e32 v60, v60, v67
	v_mul_f32_e32 v60, v60, v52
	v_mul_f32_e32 v52, v56, v68
	v_mul_f32_e32 v56, 0xbfb8aa3b, v61
	v_exp_f32_e32 v56, v56
	v_mul_f32_e32 v66, 0xbfb8aa3b, v57
	v_mul_f32_e32 v67, v52, v48
	v_exp_f32_e32 v66, v66
	v_add_f32_e32 v48, 1.0, v56
	v_rcp_f32_e32 v48, v48
	v_mul_f32_e32 v56, 0xbfb8aa3b, v62
	v_exp_f32_e32 v56, v56
	v_add_f32_e32 v52, 1.0, v66
	v_mul_f32_e32 v48, v61, v48
	v_rcp_f32_e32 v52, v52
	v_mul_f32_e32 v48, v48, v53
	v_add_f32_e32 v53, 1.0, v56
	v_rcp_f32_e32 v53, v53
	v_mul_f32_e32 v52, v57, v52
	v_mul_f32_e32 v56, 0xbfb8aa3b, v58
	v_mul_f32_e32 v57, v52, v49
	v_mul_f32_e32 v49, v62, v53
	v_exp_f32_e32 v56, v56
	v_mul_f32_e32 v49, v49, v54
	v_mul_f32_e32 v53, 0xbfb8aa3b, v63
	v_mul_f32_e32 v54, 0xbfb8aa3b, v59
	v_exp_f32_e32 v53, v53
	v_exp_f32_e32 v54, v54
	v_add_f32_e32 v52, 1.0, v56
	v_rcp_f32_e32 v52, v52
	v_add_f32_e32 v53, 1.0, v53
	v_add_f32_e32 v54, 1.0, v54
	v_rcp_f32_e32 v53, v53
	v_rcp_f32_e32 v54, v54
	v_mul_f32_e32 v52, v58, v52
	v_mul_f32_e32 v56, v52, v50
	v_mul_f32_e32 v50, v63, v53
	v_mul_f32_e32 v52, v59, v54
	v_mul_f32_e32 v50, v50, v55
	v_mul_f32_e32 v51, v52, v51
	v_lshl_add_u64 v[52:53], v[64:65], 0, v[112:113]
	s_nop 1
	v_cvt_pk_bf16_f32 v48, v60, v48
	s_nop 1
	v_cvt_pk_bf16_f32 v49, v49, v50
	s_nop 1
	v_cvt_pk_bf16_f32 v50, v67, v57
	s_nop 1
	v_cvt_pk_bf16_f32 v51, v56, v51
	flat_store_dwordx4 v[52:53], v[48:51] nt
	s_nop 1
	v_mul_f32_e32 v48, 0xbfb8aa3b, v44
	v_exp_f32_e32 v48, v48
	v_mul_f32_e32 v49, 0xbfb8aa3b, v40
	v_exp_f32_e32 v49, v49
	v_add_u32_e32 v50, 0x90, v152
	v_add_f32_e32 v48, 1.0, v48
	v_rcp_f32_e32 v51, v48
	v_add_f32_e32 v48, 1.0, v49
	v_rcp_f32_e32 v52, v48
	v_mad_i64_i32 v[48:49], s[20:21], v50, s48, v[144:145]
	v_mul_f32_e32 v44, v44, v51
	v_mul_f32_e32 v44, v44, v36
	v_mul_f32_e32 v36, v40, v52
	v_mul_f32_e32 v40, 0xbfb8aa3b, v45
	v_exp_f32_e32 v40, v40
	v_mul_f32_e32 v50, 0xbfb8aa3b, v41
	v_mul_f32_e32 v51, v36, v32
	v_exp_f32_e32 v50, v50
	v_add_f32_e32 v32, 1.0, v40
	v_rcp_f32_e32 v32, v32
	v_mul_f32_e32 v40, 0xbfb8aa3b, v46
	v_exp_f32_e32 v40, v40
	v_add_f32_e32 v36, 1.0, v50
	v_mul_f32_e32 v32, v45, v32
	v_rcp_f32_e32 v36, v36
	v_mul_f32_e32 v32, v32, v37
	v_add_f32_e32 v37, 1.0, v40
; __device__ __forceinline__ float fsilu(float x) { return x * fsigmoid(x); }
; __device__ __forceinline__ u32x4 pack8(f32x4 a, f32x4 b) { u32x4 w; w.x = cvt_pk_bf16(a[0], a[1]); w.y = cvt_pk_bf16(a[2], a[3]); w.z = cvt_pk_bf16(b[0], b[1]); w.w = cvt_pk_bf16(b[2], b[3]); return w; }
; #define PG8_BAR __builtin_amdgcn_s_barrier()
; template <class Epi>
; __device__ __forceinline__ void gemm_phase(ldsp lds, const Gemm g, const StaticOrder& S, const Epi& E, int wave0) {
;     ...
;         if (!has_next) break;
; #pragma unroll
;         for (int a = 0; a < 2; ++a)
; #pragma unroll
;             for (int b = 0; b < 2; ++b)
; #pragma unroll
;                 for (int m = 0; m < 4; ++m)
; #pragma unroll
;                     for (int n = 0; n < 2; ++n) acc[a][b][m][n] = (f32x4){0.f, 0.f, 0.f, 0.f};
;         cur = nxt; cA = nA; cB = nB; ++ui;
;         if (wr == 1) PG8_BAR;
;     __device__ __forceinline__ void operator()(AccRef acc, const Unit& u, int wr, int wc, int fr, int fq) const {
;     ...
;         for (int ai = 0; ai < 2; ++ai)
; #pragma unroll
;             for (int m = 0; m < 4; ++m) {
;                 bf16_t* p = O + (size_t)(row0 + ai * HALF + m * 16) * FF + col0;
;                 f32x4 v0, v1;
; #pragma unroll
;                 for (int j = 0; j < 4; ++j) { v0[j] = fsilu(acc[ai][0][m][0][j]) * acc[ai][1][m][0][j]; v1[j] = fsilu(acc[ai][0][m][1][j]) * acc[ai][1][m][1][j]; }
;                 *(u32x4*)p = pack8(v0, v1);
	v_rcp_f32_e32 v37, v37
	v_mul_f32_e32 v36, v41, v36
	v_mul_f32_e32 v40, 0xbfb8aa3b, v42
	v_mul_f32_e32 v41, v36, v33
	v_mul_f32_e32 v33, v46, v37
	v_exp_f32_e32 v40, v40
	v_mul_f32_e32 v33, v33, v38
	v_mul_f32_e32 v37, 0xbfb8aa3b, v47
	v_mul_f32_e32 v38, 0xbfb8aa3b, v43
	v_exp_f32_e32 v37, v37
	v_exp_f32_e32 v38, v38
	v_add_f32_e32 v36, 1.0, v40
	v_rcp_f32_e32 v36, v36
	v_add_f32_e32 v37, 1.0, v37
	v_add_f32_e32 v38, 1.0, v38
	v_rcp_f32_e32 v37, v37
	v_rcp_f32_e32 v38, v38
	v_mul_f32_e32 v36, v42, v36
	v_mul_f32_e32 v40, v36, v34
	v_mul_f32_e32 v34, v47, v37
	v_mul_f32_e32 v36, v43, v38
	v_mul_f32_e32 v34, v34, v39
	v_mul_f32_e32 v35, v36, v35
	v_lshl_add_u64 v[36:37], v[48:49], 0, v[112:113]
	s_nop 1
	v_cvt_pk_bf16_f32 v32, v44, v32
	s_nop 1
	v_cvt_pk_bf16_f32 v33, v33, v34
	s_nop 1
	v_cvt_pk_bf16_f32 v34, v51, v41
	s_nop 1
	v_cvt_pk_bf16_f32 v35, v40, v35
	flat_store_dwordx4 v[36:37], v[32:35] nt
	s_nop 1
	v_mul_f32_e32 v32, 0xbfb8aa3b, v28
	v_exp_f32_e32 v32, v32
	v_mul_f32_e32 v33, 0xbfb8aa3b, v24
	v_exp_f32_e32 v33, v33
	v_add_u32_e32 v34, 0xa0, v152
	v_add_f32_e32 v32, 1.0, v32
	v_rcp_f32_e32 v35, v32
	v_add_f32_e32 v32, 1.0, v33
	v_rcp_f32_e32 v36, v32
	v_mad_i64_i32 v[32:33], s[20:21], v34, s48, v[144:145]
	v_mul_f32_e32 v28, v28, v35
	v_mul_f32_e32 v28, v28, v20
	v_mul_f32_e32 v20, v24, v36
	v_mul_f32_e32 v24, 0xbfb8aa3b, v29
	v_exp_f32_e32 v24, v24
	v_mul_f32_e32 v34, 0xbfb8aa3b, v25
	v_mul_f32_e32 v35, v20, v16
	v_exp_f32_e32 v34, v34
	v_add_f32_e32 v16, 1.0, v24
	v_rcp_f32_e32 v16, v16
	v_mul_f32_e32 v24, 0xbfb8aa3b, v30
	v_exp_f32_e32 v24, v24
	v_add_f32_e32 v20, 1.0, v34
	v_mul_f32_e32 v16, v29, v16
	v_rcp_f32_e32 v20, v20
	v_mul_f32_e32 v16, v16, v21
	v_add_f32_e32 v21, 1.0, v24
	v_rcp_f32_e32 v21, v21
	v_mul_f32_e32 v20, v25, v20
	v_mul_f32_e32 v24, 0xbfb8aa3b, v26
	v_mul_f32_e32 v25, v20, v17
	v_mul_f32_e32 v17, v30, v21
	v_exp_f32_e32 v24, v24
	v_mul_f32_e32 v17, v17, v22
	v_mul_f32_e32 v21, 0xbfb8aa3b, v31
	v_mul_f32_e32 v22, 0xbfb8aa3b, v27
	v_exp_f32_e32 v21, v21
	v_exp_f32_e32 v22, v22
	v_add_f32_e32 v20, 1.0, v24
	v_rcp_f32_e32 v20, v20
	v_add_f32_e32 v21, 1.0, v21
	v_add_f32_e32 v22, 1.0, v22
	v_rcp_f32_e32 v21, v21
	v_rcp_f32_e32 v22, v22
	v_mul_f32_e32 v20, v26, v20
	v_mul_f32_e32 v24, v20, v18
	v_mul_f32_e32 v18, v31, v21
	v_mul_f32_e32 v20, v27, v22
	v_mul_f32_e32 v18, v18, v23
	v_mul_f32_e32 v19, v20, v19
	v_lshl_add_u64 v[20:21], v[32:33], 0, v[112:113]
	s_nop 1
	v_cvt_pk_bf16_f32 v16, v28, v16
	s_nop 1
	v_cvt_pk_bf16_f32 v17, v17, v18
	s_nop 1
	v_cvt_pk_bf16_f32 v18, v35, v25
	s_nop 1
	v_cvt_pk_bf16_f32 v19, v24, v19
	flat_store_dwordx4 v[20:21], v[16:19] nt
	s_nop 1
	v_mul_f32_e32 v16, 0xbfb8aa3b, v12
	v_exp_f32_e32 v16, v16
	v_mul_f32_e32 v17, 0xbfb8aa3b, v8
	v_exp_f32_e32 v17, v17
	v_add_u32_e32 v18, 0xb0, v152
	v_add_f32_e32 v16, 1.0, v16
	v_rcp_f32_e32 v19, v16
	v_add_f32_e32 v16, 1.0, v17
	v_rcp_f32_e32 v20, v16
	v_mad_i64_i32 v[16:17], s[20:21], v18, s48, v[144:145]
	v_mul_f32_e32 v12, v12, v19
	v_mul_f32_e32 v12, v12, v4
	v_mul_f32_e32 v4, v8, v20
	v_mul_f32_e32 v8, 0xbfb8aa3b, v13
	v_exp_f32_e32 v8, v8
	v_mul_f32_e32 v18, 0xbfb8aa3b, v9
	v_mul_f32_e32 v19, v4, v0
	v_exp_f32_e32 v18, v18
	v_add_f32_e32 v0, 1.0, v8
	v_rcp_f32_e32 v0, v0
	v_mul_f32_e32 v8, 0xbfb8aa3b, v14
	v_exp_f32_e32 v8, v8
	v_add_f32_e32 v4, 1.0, v18
	v_mul_f32_e32 v0, v13, v0
	v_rcp_f32_e32 v4, v4
	v_mul_f32_e32 v0, v0, v5
	v_add_f32_e32 v5, 1.0, v8
	v_rcp_f32_e32 v5, v5
	v_mul_f32_e32 v4, v9, v4
	v_mul_f32_e32 v8, 0xbfb8aa3b, v10
	v_mul_f32_e32 v9, v4, v1
	v_mul_f32_e32 v1, v14, v5
	v_exp_f32_e32 v8, v8
	v_mul_f32_e32 v1, v1, v6
	v_mul_f32_e32 v5, 0xbfb8aa3b, v15
	v_mul_f32_e32 v6, 0xbfb8aa3b, v11
	v_exp_f32_e32 v5, v5
	v_exp_f32_e32 v6, v6
	v_add_f32_e32 v4, 1.0, v8
	v_rcp_f32_e32 v4, v4
	v_add_f32_e32 v5, 1.0, v5
	v_add_f32_e32 v6, 1.0, v6
	v_rcp_f32_e32 v5, v5
	v_rcp_f32_e32 v6, v6
	v_mul_f32_e32 v4, v10, v4
	v_mul_f32_e32 v8, v4, v2
	v_mul_f32_e32 v2, v15, v5
	v_mul_f32_e32 v4, v11, v6
	v_mul_f32_e32 v2, v2, v7
	v_mul_f32_e32 v3, v4, v3
	v_lshl_add_u64 v[4:5], v[16:17], 0, v[112:113]
	s_nop 1
	v_cvt_pk_bf16_f32 v0, v12, v0
	s_nop 1
	v_cvt_pk_bf16_f32 v1, v1, v2
	s_nop 1
	v_cvt_pk_bf16_f32 v2, v19, v9
	s_nop 1
	v_cvt_pk_bf16_f32 v3, v8, v3
	flat_store_dwordx4 v[4:5], v[0:3] nt
	s_cbranch_vccnz .LBB0_885
	s_andn2_b64 vcc, exec, s[2:3]
	s_cbranch_vccnz .LBB0_884
	s_barrier
	s_branch .LBB0_884

; __device__ __forceinline__ void ln_phase(float* io, const float* g, const float* b, bf16_t* hb, float* stats, int gw, int NGW, int lane) {
;     ...
;     for (int row = gw; row < M; row += NGW) {
;         f32x4* xr = (f32x4*)(io + (size_t)row * D) + lane;
;         f32x4 v[8]; float s = 0.f;
; #pragma unroll
;         for (int j = 0; j < 8; ++j) { v[j] = xr[64 * j]; s += (v[j][0] + v[j][1]) + (v[j][2] + v[j][3]); }
;         const float mean = wave_sum(s, lane) * (1.f / D); float s2 = 0.f;
; #pragma unroll
;         for (int j = 0; j < 8; ++j) { v[j] = v[j] - mean; s2 += (v[j][0] * v[j][0] + v[j][1] * v[j][1]) + (v[j][2] * v[j][2] + v[j][3] * v[j][3]); }
;         const float rstd = 1.0f / sqrtf(wave_sum(s2, lane) * (1.f / D) + 1e-5f);
.LBB0_1152:
	flat_load_dwordx4 v[84:87], v[96:97] nt
	flat_load_dwordx4 v[64:67], v[96:97] offset:1024 nt
	flat_load_dwordx4 v[92:95], v[96:97] offset:2048 nt
	flat_load_dwordx4 v[76:79], v[96:97] offset:3072 nt
	v_add_co_u32_e32 v98, vcc, s3, v96
	s_add_i32 s2, s2, s58
	s_nop 0
	v_addc_co_u32_e32 v99, vcc, 0, v97, vcc
	flat_load_dwordx4 v[72:75], v[98:99] nt
	flat_load_dwordx4 v[80:83], v[98:99] offset:1024 nt
	flat_load_dwordx4 v[88:91], v[98:99] offset:2048 nt
	flat_load_dwordx4 v[68:71], v[98:99] offset:3072 nt
	s_cmp_lt_i32 s2, 0x8000
	s_waitcnt vmcnt(0) lgkmcnt(0)
	v_mov_b32_e32 v108, v84
	v_mov_b32_e32 v109, v64
	v_mov_b32_e32 v110, v85
	v_mov_b32_e32 v111, v65
	v_mov_b32_e32 v112, v86
	v_mov_b32_e32 v113, v66
	v_mov_b32_e32 v114, v87
	v_mov_b32_e32 v115, v67
	v_mov_b32_e32 v116, v93
	v_mov_b32_e32 v117, v94
	v_mov_b32_e32 v118, v92
	v_mov_b32_e32 v119, v95
	v_pk_add_f32 v[108:109], v[108:109], v[110:111]
	v_pk_add_f32 v[110:111], v[112:113], v[114:115]
	v_pk_add_f32 v[112:113], v[116:117], v[118:119]
	v_pk_add_f32 v[108:109], v[108:109], v[110:111]
	v_pk_add_f32 v[110:111], v[112:113], v[112:113] op_sel:[0,1] op_sel_hi:[1,0]
	v_add_f32_e32 v108, 0, v108
	v_add_f32_e32 v120, v76, v77
	v_add_f32_e32 v122, v78, v79
	v_mov_b32_e32 v115, v72
	v_mov_b32_e32 v121, v74
	v_mov_b32_e32 v123, v75
	v_mov_b32_e32 v111, v73
	v_add_f32_e32 v114, v108, v109
	v_mov_b32_e32 v116, v81
	v_mov_b32_e32 v117, v82
	v_mov_b32_e32 v118, v80
	v_mov_b32_e32 v119, v83
	v_pk_add_f32 v[112:113], v[120:121], v[122:123]
	v_pk_add_f32 v[108:109], v[114:115], v[110:111]
	v_pk_add_f32 v[116:117], v[116:117], v[118:119]
	v_pk_add_f32 v[108:109], v[108:109], v[112:113]
	v_pk_add_f32 v[116:117], v[116:117], v[116:117] op_sel:[0,1] op_sel_hi:[1,0]
	v_pk_add_f32 v[108:109], v[108:109], v[108:109] op_sel:[0,1] op_sel_hi:[1,0]
	v_add_f32_e32 v124, v88, v89
	v_add_f32_e32 v126, v90, v91
	v_mov_b32_e32 v125, v70
	v_mov_b32_e32 v127, v71
	v_mov_b32_e32 v117, v69
	v_mov_b32_e32 v109, v68
	v_pk_add_f32 v[118:119], v[124:125], v[126:127]
	v_pk_add_f32 v[108:109], v[108:109], v[116:117]
	s_nop 0
	v_pk_add_f32 v[108:109], v[108:109], v[118:119]
	s_nop 0
	v_add_f32_e32 v108, v108, v109
	ds_bpermute_b32 v109, v100, v108
	s_waitcnt lgkmcnt(0)
	v_add_f32_e32 v108, v108, v109
	ds_bpermute_b32 v109, v101, v108
	s_waitcnt lgkmcnt(0)
	v_add_f32_e32 v108, v108, v109
	ds_bpermute_b32 v109, v102, v108
	s_waitcnt lgkmcnt(0)
	v_add_f32_e32 v108, v108, v109
	ds_bpermute_b32 v109, v103, v108
	s_waitcnt lgkmcnt(0)
	v_add_f32_e32 v108, v108, v109
	ds_bpermute_b32 v109, v104, v108
	s_waitcnt lgkmcnt(0)
	v_add_f32_e32 v108, v108, v109
	ds_bpermute_b32 v109, v105, v108
	s_waitcnt lgkmcnt(0)
	v_add_f32_e32 v129, v108, v109
	v_fmamk_f32 v87, v129, 0xba000000, v87
	v_fmamk_f32 v85, v129, 0xba000000, v85
	v_fmamk_f32 v67, v129, 0xba000000, v67
	v_fmamk_f32 v65, v129, 0xba000000, v65
	v_fmamk_f32 v86, v129, 0xba000000, v86
	v_fmac_f32_e32 v84, 0xba000000, v129
	v_fmamk_f32 v66, v129, 0xba000000, v66
	v_fmac_f32_e32 v64, 0xba000000, v129
	v_fmamk_f32 v93, v129, 0xba000000, v93
	v_fmamk_f32 v92, v129, 0xba000000, v92
	v_fmamk_f32 v95, v129, 0xba000000, v95
	v_fmac_f32_e32 v94, 0xba000000, v129
	v_fmamk_f32 v111, v129, 0xba000000, v81
	v_fmamk_f32 v110, v129, 0xba000000, v80
	v_mov_b32_e32 v80, v85
	v_mov_b32_e32 v81, v65
	v_mov_b32_e32 v114, v87
	v_mov_b32_e32 v115, v67
	v_fmamk_f32 v109, v129, 0xba000000, v75
	v_fmamk_f32 v108, v129, 0xba000000, v74
	v_mov_b32_e32 v74, v84
	v_mov_b32_e32 v75, v64
	v_mov_b32_e32 v112, v86
	v_mov_b32_e32 v113, v66
	v_pk_mul_f32 v[116:117], v[94:95], v[94:95]
	v_pk_mul_f32 v[118:119], v[92:93], v[92:93]
	v_pk_mul_f32 v[80:81], v[80:81], v[80:81]
	v_pk_mul_f32 v[114:115], v[114:115], v[114:115]
	v_fmamk_f32 v76, v129, 0xba000000, v76
	v_fmac_f32_e32 v78, 0xba000000, v129
	v_pk_mov_b32 v[132:133], v[118:119], v[116:117] op_sel:[1,0]
	v_mov_b32_e32 v119, v117
	v_pk_fma_f32 v[74:75], v[74:75], v[74:75], v[80:81]
	v_pk_fma_f32 v[80:81], v[112:113], v[112:113], v[114:115]
	v_fmamk_f32 v77, v129, 0xba000000, v77
	v_fmamk_f32 v79, v129, 0xba000000, v79
	v_mul_f32_e32 v120, v76, v76
	v_mul_f32_e32 v122, v78, v78
	v_pk_add_f32 v[112:113], v[132:133], v[118:119]
	v_pk_add_f32 v[74:75], v[74:75], v[80:81]
	v_fmamk_f32 v73, v129, 0xba000000, v73
	v_fmac_f32_e32 v72, 0xba000000, v129
	v_fmamk_f32 v83, v129, 0xba000000, v83
	v_fmac_f32_e32 v82, 0xba000000, v129
	v_pk_fma_f32 v[116:117], v[76:77], v[76:77], v[120:121] op_sel_hi:[1,1,0]
	v_pk_fma_f32 v[120:121], v[78:79], v[78:79], v[122:123] op_sel_hi:[1,1,0]
	v_pk_add_f32 v[80:81], v[112:113], v[112:113] op_sel_hi:[0,1]
	v_pk_add_f32 v[74:75], v[74:75], v[74:75] op_sel_hi:[0,1]
	v_pk_mul_f32 v[124:125], v[82:83], v[82:83]
	v_pk_mul_f32 v[126:127], v[110:111], v[110:111]
	v_mul_f32_e32 v116, v72, v72
	v_mul_f32_e32 v120, v73, v73
	v_mul_f32_e32 v80, v108, v108
	v_mul_f32_e32 v74, v109, v109
	v_fmamk_f32 v88, v129, 0xba000000, v88
	v_fmac_f32_e32 v90, 0xba000000, v129
	v_pk_mov_b32 v[122:123], v[126:127], v[124:125] op_sel:[1,0]
	v_mov_b32_e32 v127, v125
	v_pk_add_f32 v[112:113], v[116:117], v[120:121]
	v_pk_add_f32 v[74:75], v[80:81], v[74:75]
	v_fmamk_f32 v89, v129, 0xba000000, v89
	v_fmamk_f32 v91, v129, 0xba000000, v91
	v_mul_f32_e32 v128, v88, v88
	v_mul_f32_e32 v130, v90, v90
	v_pk_add_f32 v[114:115], v[122:123], v[126:127]
	v_pk_add_f32 v[74:75], v[112:113], v[74:75]
	v_pk_fma_f32 v[124:125], v[88:89], v[88:89], v[128:129] op_sel_hi:[1,1,0]
	v_pk_add_f32 v[114:115], v[114:115], v[114:115] op_sel_hi:[0,1]
	v_pk_add_f32 v[74:75], v[74:75], v[74:75] op_sel_hi:[0,1]
	v_pk_fma_f32 v[80:81], v[90:91], v[90:91], v[130:131] op_sel_hi:[1,1,0]
	v_fmamk_f32 v113, v129, 0xba000000, v71
	v_fmamk_f32 v112, v129, 0xba000000, v70
	v_fmamk_f32 v69, v129, 0xba000000, v69
	v_fmac_f32_e32 v68, 0xba000000, v129
	v_mul_f32_e32 v124, v68, v68
	v_mul_f32_e32 v80, v69, v69
	v_mul_f32_e32 v114, v112, v112
	v_mul_f32_e32 v74, v113, v113
	v_pk_add_f32 v[70:71], v[124:125], v[80:81]
	v_pk_add_f32 v[74:75], v[114:115], v[74:75]
	s_nop 0
	v_pk_add_f32 v[70:71], v[70:71], v[74:75]
	s_nop 0
	v_add_f32_e32 v70, v70, v71
	ds_bpermute_b32 v71, v100, v70
	s_waitcnt lgkmcnt(0)
; __device__ __forceinline__ unsigned cvt_pk_bf16(float lo, float hi) { unsigned r; asm volatile("s_nop 1\n\tv_cvt_pk_bf16_f32 %0, %1, %2" : "=v"(r) : "v"(lo), "v"(hi)); return r; }
; __device__ __forceinline__ void ln_phase(float* io, const float* g, const float* b, bf16_t* hb, float* stats, int gw, int NGW, int lane) {
;     ...
;         const float mean = wave_sum(s, lane) * (1.f / D); float s2 = 0.f;
; #pragma unroll
;         for (int j = 0; j < 8; ++j) { v[j] = v[j] - mean; s2 += (v[j][0] * v[j][0] + v[j][1] * v[j][1]) + (v[j][2] * v[j][2] + v[j][3] * v[j][3]); }
;         const float rstd = 1.0f / sqrtf(wave_sum(s2, lane) * (1.f / D) + 1e-5f);
; #pragma unroll
;         for (int j = 0; j < 8; ++j) v[j] = v[j] * rstd * gv[j] + bv[j];
;         if (stats) {
;             u32x2* o8 = (u32x2*)(hb + (size_t)row * D) + lane;
; #pragma unroll
;             for (int j = 0; j < 8; ++j) { u32x2 w; w.x = cvt_pk_bf16(v[j][0], v[j][1]); w.y = cvt_pk_bf16(v[j][2], v[j][3]); o8[64 * j] = w; }
;         } else {
; #pragma unroll
;             for (int j = 0; j < 8; ++j) xr[64 * j] = v[j];
	v_add_f32_e32 v70, v70, v71
	ds_bpermute_b32 v71, v101, v70
	s_waitcnt lgkmcnt(0)
	v_add_f32_e32 v70, v70, v71
	ds_bpermute_b32 v71, v102, v70
	s_waitcnt lgkmcnt(0)
	v_add_f32_e32 v70, v70, v71
	ds_bpermute_b32 v71, v103, v70
	s_waitcnt lgkmcnt(0)
	v_add_f32_e32 v70, v70, v71
	ds_bpermute_b32 v71, v104, v70
	s_waitcnt lgkmcnt(0)
	v_add_f32_e32 v70, v70, v71
	ds_bpermute_b32 v71, v105, v70
	s_waitcnt lgkmcnt(0)
	v_add_f32_e32 v70, v70, v71
	v_fmamk_f32 v70, v70, 0x3a000000, v106
	v_mul_f32_e32 v71, 0x4f800000, v70
	v_cmp_gt_f32_e32 vcc, s6, v70
	s_nop 1
	v_cndmask_b32_e32 v70, v70, v71, vcc
	v_sqrt_f32_e32 v71, v70
	s_nop 0
	v_add_u32_e32 v74, -1, v71
	v_add_u32_e32 v75, 1, v71
	v_fma_f32 v80, -v74, v71, v70
	v_fma_f32 v81, -v75, v71, v70
	v_cmp_ge_f32_e64 s[0:1], 0, v80
	s_nop 1
	v_cndmask_b32_e64 v71, v71, v74, s[0:1]
	v_cmp_lt_f32_e64 s[0:1], 0, v81
	s_nop 1
	v_cndmask_b32_e64 v71, v71, v75, s[0:1]
	v_mul_f32_e32 v74, 0x37800000, v71
	v_cndmask_b32_e32 v71, v71, v74, vcc
	v_cmp_class_f32_e32 vcc, v70, v107
	s_nop 1
	v_cndmask_b32_e32 v70, v71, v70, vcc
	v_div_scale_f32 v71, s[0:1], v70, v70, 1.0
	v_rcp_f32_e32 v74, v71
	v_div_scale_f32 v75, vcc, 1.0, v70, 1.0
	v_fma_f32 v80, -v71, v74, 1.0
	v_fmac_f32_e32 v74, v80, v74
	v_mul_f32_e32 v80, v75, v74
	v_fma_f32 v81, -v71, v80, v75
	v_fmac_f32_e32 v80, v81, v74
	v_fma_f32 v71, -v71, v80, v75
	v_div_fmas_f32 v71, v71, v74, v80
	v_div_fixup_f32 v114, v71, v70, 1.0
	v_pk_mul_f32 v[70:71], v[84:85], v[114:115] op_sel_hi:[1,0]
	v_pk_mul_f32 v[74:75], v[86:87], v[114:115] op_sel_hi:[1,0]
	v_pk_mul_f32 v[86:87], v[94:95], v[114:115] op_sel_hi:[1,0]
	v_pk_mul_f32 v[94:95], v[76:77], v[114:115] op_sel_hi:[1,0]
	v_pk_mul_f32 v[82:83], v[82:83], v[114:115] op_sel_hi:[1,0]
	v_pk_mul_f32 v[80:81], v[64:65], v[114:115] op_sel_hi:[1,0]
	v_pk_mul_f32 v[84:85], v[66:67], v[114:115] op_sel_hi:[1,0]
	v_pk_mul_f32 v[92:93], v[92:93], v[114:115] op_sel_hi:[1,0]
	v_pk_fma_f32 v[64:65], v[0:1], v[70:71], v[4:5]
	v_pk_mul_f32 v[70:71], v[78:79], v[114:115] op_sel_hi:[1,0]
	v_pk_fma_f32 v[78:79], v[24:25], v[94:95], v[28:29]
	v_pk_fma_f32 v[94:95], v[38:39], v[82:83], v[46:47]
	v_pk_mul_f32 v[82:83], v[88:89], v[114:115] op_sel_hi:[1,0]
	v_pk_mul_f32 v[88:89], v[90:91], v[114:115] op_sel_hi:[1,0]
	v_pk_fma_f32 v[66:67], v[2:3], v[74:75], v[6:7]
	v_pk_fma_f32 v[76:77], v[10:11], v[84:85], v[18:19]
	v_pk_fma_f32 v[74:75], v[8:9], v[80:81], v[16:17]
	v_pk_fma_f32 v[84:85], v[12:13], v[92:93], v[20:21]
	v_pk_fma_f32 v[80:81], v[26:27], v[70:71], v[30:31]
	v_pk_mul_f32 v[70:71], v[72:73], v[114:115] op_sel_hi:[1,0]
	v_pk_mul_f32 v[72:73], v[108:109], v[114:115] op_sel_hi:[1,0]
	v_pk_mul_f32 v[92:93], v[110:111], v[114:115] op_sel_hi:[1,0]
	v_pk_fma_f32 v[90:91], v[50:51], v[88:89], v[58:59]
	v_pk_fma_f32 v[88:89], v[48:49], v[82:83], v[56:57]
	v_pk_mul_f32 v[68:69], v[68:69], v[114:115] op_sel_hi:[1,0]
	v_pk_mul_f32 v[82:83], v[112:113], v[114:115] op_sel_hi:[1,0]
	v_pk_fma_f32 v[86:87], v[14:15], v[86:87], v[22:23]
	v_pk_fma_f32 v[72:73], v[34:35], v[72:73], v[42:43]
	v_pk_fma_f32 v[70:71], v[32:33], v[70:71], v[40:41]
	v_pk_fma_f32 v[92:93], v[36:37], v[92:93], v[44:45]
	v_pk_fma_f32 v[110:111], v[54:55], v[82:83], v[62:63]
	v_pk_fma_f32 v[108:109], v[52:53], v[68:69], v[60:61]
	flat_store_dwordx4 v[96:97], v[64:67] nt
	flat_store_dwordx4 v[96:97], v[74:77] offset:1024 nt
	flat_store_dwordx4 v[96:97], v[84:87] offset:2048 nt
	flat_store_dwordx4 v[96:97], v[78:81] offset:3072 nt
	flat_store_dwordx4 v[98:99], v[70:73] nt
	flat_store_dwordx4 v[98:99], v[92:95] offset:1024 nt
	flat_store_dwordx4 v[98:99], v[88:91] offset:2048 nt
	flat_store_dwordx4 v[98:99], v[108:111] offset:3072 nt
	v_lshl_add_u64 v[96:97], v[96:97], 0, s[4:5]
	s_cbranch_scc1 .LBB0_1152
